# out-projection residual epilogue de-serialised: the four residual loads of each row block issued together with one wait instead of a load-wait-add-store ladder
# speedup vs baseline: 1.0089x; 1.0089x over previous
;     __device__ __forceinline__ void operator()(const f32x4 (&acc)[2][2][4][2], const Unit& u, int wr, int wc, int fr, int fq) const {
;     ...
;             for (int m = 0; m < 4; ++m) { const int r = row0 + ai * HALF + m * 16;
;                 if (r < lrows) {
;                     const float* rp = (r < nmeta) ? res_meta + (size_t)r * ldc : res_body + (size_t)(r - nmeta) * ldc;
;                     float* op = (r < nmeta) ? out_meta : out_body;
;                     if (op) { op += (r < nmeta) ? (size_t)r * ldc : (size_t)(r - nmeta) * ldc;
; #pragma unroll
;                     for (int bj = 0; bj < 2; ++bj)
; #pragma unroll
;                         for (int n = 0; n < 2; ++n) { const int c = col0 + bj * HALF + n * 16; const f32x4 b = *(const f32x4*)(rp + c); *(f32x4*)(op + c) = b + acc[ai][bj][m][n]; } } } }
.LBB0_899:
	v_lshl_add_u32 v146, s55, 8, v142
	s_movk_i32 s2, 0x4010
	v_lshl_or_b32 v138, s21, 8, v144
	v_cmp_gt_i32_e32 vcc, s2, v146
	s_and_saveexec_b64 s[0:1], vcc
	s_cbranch_execz .LBB0_902
	v_readlane_b32 s24, v254, 11
	v_readlane_b32 s27, v254, 14
	v_readlane_b32 s26, v254, 13
	v_mov_b32_e32 v140, s50
	v_mov_b32_e32 v139, s27
	v_cmp_gt_i32_e32 vcc, 16, v146
	v_readlane_b32 s25, v254, 12
	s_nop 0
	v_cndmask_b32_e32 v141, v139, v140, vcc
	v_mov_b32_e32 v139, s26
	v_mov_b32_e32 v140, s51
	v_cndmask_b32_e32 v140, v139, v140, vcc
	v_cmp_ne_u64_e64 s[38:39], 0, v[140:141]
	s_and_b64 exec, exec, s[38:39]
	s_cbranch_execz .LBB0_902
	v_readlane_b32 s6, v255, 5
	v_readlane_b32 s7, v255, 6
	s_nop 1
	v_mov_b32_e32 v139, s7
	v_readlane_b32 s7, v255, 3
	s_nop 1
	v_mov_b32_e32 v147, s7
	v_cndmask_b32_e32 v149, v139, v147, vcc
	v_mov_b32_e32 v139, s6
	v_readlane_b32 s6, v255, 4
	s_nop 1
	v_mov_b32_e32 v147, s6
	v_cndmask_b32_e32 v148, v139, v147, vcc
	v_ashrrev_i32_e32 v139, 31, v146
	v_add_u32_e32 v147, -16, v146
	v_cndmask_b32_e32 v151, 0, v139, vcc
	v_cndmask_b32_e32 v150, v147, v146, vcc
	v_lshlrev_b64 v[150:151], 13, v[150:151]
	v_ashrrev_i32_e32 v139, 31, v138
	v_lshl_add_u64 v[148:149], v[148:149], 0, v[150:151]
	v_lshlrev_b64 v[152:153], 2, v[138:139]
	v_lshl_add_u64 v[154:155], v[148:149], 0, v[152:153]
	v_lshl_add_u64 v[140:141], v[140:141], 0, v[150:151]
	global_load_dwordx4 v[148:151], v[154:155], off
	global_load_dwordx4 v[172:175], v[154:155], off offset:64
	global_load_dwordx4 v[176:179], v[154:155], off offset:512
	global_load_dwordx4 v[186:189], v[154:155], off offset:576
	v_lshl_add_u64 v[140:141], v[140:141], 0, v[152:153]
	s_waitcnt vmcnt(0)
	v_pk_add_f32 v[130:131], v[130:131], v[150:151]
	v_pk_add_f32 v[128:129], v[128:129], v[148:149]
	global_store_dwordx4 v[140:141], v[128:131], off


;     __device__ __forceinline__ void operator()(const f32x4 (&acc)[2][2][4][2], const Unit& u, int wr, int wc, int fr, int fq) const {
;     ...
;                         for (int n = 0; n < 2; ++n) { const int c = col0 + bj * HALF + n * 16; const f32x4 b = *(const f32x4*)(rp + c); *(f32x4*)(op + c) = b + acc[ai][bj][m][n]; } } } }
	v_pk_add_f32 v[126:127], v[126:127], v[174:175]
	v_pk_add_f32 v[124:125], v[124:125], v[172:173]
	global_store_dwordx4 v[140:141], v[124:127], off offset:64


;     __device__ __forceinline__ void operator()(const f32x4 (&acc)[2][2][4][2], const Unit& u, int wr, int wc, int fr, int fq) const {
;     ...
;                         for (int n = 0; n < 2; ++n) { const int c = col0 + bj * HALF + n * 16; const f32x4 b = *(const f32x4*)(rp + c); *(f32x4*)(op + c) = b + acc[ai][bj][m][n]; } } } }
	v_pk_add_f32 v[122:123], v[122:123], v[178:179]
	v_pk_add_f32 v[120:121], v[120:121], v[176:177]
	global_store_dwordx4 v[140:141], v[120:123], off offset:512


;     __device__ __forceinline__ void operator()(const f32x4 (&acc)[2][2][4][2], const Unit& u, int wr, int wc, int fr, int fq) const {
;     ...
;             for (int m = 0; m < 4; ++m) { const int r = row0 + ai * HALF + m * 16;
;                 if (r < lrows) {
;                     const float* rp = (r < nmeta) ? res_meta + (size_t)r * ldc : res_body + (size_t)(r - nmeta) * ldc;
;                     float* op = (r < nmeta) ? out_meta : out_body;
;                     if (op) { op += (r < nmeta) ? (size_t)r * ldc : (size_t)(r - nmeta) * ldc;
; #pragma unroll
;                     for (int bj = 0; bj < 2; ++bj)
; #pragma unroll
;                         for (int n = 0; n < 2; ++n) { const int c = col0 + bj * HALF + n * 16; const f32x4 b = *(const f32x4*)(rp + c); *(f32x4*)(op + c) = b + acc[ai][bj][m][n]; } } } }
	v_pk_add_f32 v[118:119], v[118:119], v[188:189]
	v_pk_add_f32 v[116:117], v[116:117], v[186:187]
	global_store_dwordx4 v[140:141], v[116:119], off offset:576
.LBB0_902:
	s_or_b64 exec, exec, s[0:1]
	s_nop 0
	v_or_b32_e32 v118, 16, v146
	v_cmp_gt_i32_e32 vcc, s2, v118
	s_and_saveexec_b64 s[0:1], vcc
	s_cbranch_execz .LBB0_905
	v_readlane_b32 s24, v254, 11
	v_readlane_b32 s27, v254, 14
	v_readlane_b32 s26, v254, 13
	v_mov_b32_e32 v117, s50
	v_mov_b32_e32 v116, s27
	v_cmp_gt_i32_e32 vcc, 0, v146
	v_mov_b32_e32 v119, s51
	v_readlane_b32 s25, v254, 12
	v_cndmask_b32_e32 v117, v116, v117, vcc
	v_mov_b32_e32 v116, s26
	v_cndmask_b32_e32 v116, v116, v119, vcc
	v_cmp_ne_u64_e64 s[38:39], 0, v[116:117]
	s_and_b64 exec, exec, s[38:39]
	s_cbranch_execz .LBB0_905
	v_readlane_b32 s6, v255, 5
	v_readlane_b32 s7, v255, 6
	v_cndmask_b32_e32 v122, v146, v118, vcc
	v_ashrrev_i32_e32 v139, 31, v138
	v_mov_b32_e32 v119, s7
	v_readlane_b32 s7, v255, 3
	v_lshlrev_b64 v[124:125], 2, v[138:139]
	s_nop 0
	v_mov_b32_e32 v120, s7
	v_cndmask_b32_e32 v121, v119, v120, vcc
	v_mov_b32_e32 v119, s6
	v_readlane_b32 s6, v255, 4
	s_nop 1
	v_mov_b32_e32 v120, s6
	v_cndmask_b32_e32 v120, v119, v120, vcc
	v_ashrrev_i32_e32 v119, 31, v118
	v_cndmask_b32_e32 v123, 0, v119, vcc
	v_lshlrev_b64 v[122:123], 13, v[122:123]
	v_lshl_add_u64 v[120:121], v[120:121], 0, v[122:123]
	v_lshl_add_u64 v[126:127], v[120:121], 0, v[124:125]
	v_lshl_add_u64 v[116:117], v[116:117], 0, v[122:123]
	global_load_dwordx4 v[120:123], v[126:127], off
	global_load_dwordx4 v[172:175], v[126:127], off offset:64
	global_load_dwordx4 v[176:179], v[126:127], off offset:512
	global_load_dwordx4 v[186:189], v[126:127], off offset:576
	v_lshl_add_u64 v[116:117], v[116:117], 0, v[124:125]
	s_waitcnt vmcnt(0)
	v_pk_add_f32 v[114:115], v[114:115], v[122:123]
	v_pk_add_f32 v[112:113], v[112:113], v[120:121]
	global_store_dwordx4 v[116:117], v[112:115], off


;     __device__ __forceinline__ void operator()(const f32x4 (&acc)[2][2][4][2], const Unit& u, int wr, int wc, int fr, int fq) const {
;     ...
;                         for (int n = 0; n < 2; ++n) { const int c = col0 + bj * HALF + n * 16; const f32x4 b = *(const f32x4*)(rp + c); *(f32x4*)(op + c) = b + acc[ai][bj][m][n]; } } } }
	v_pk_add_f32 v[110:111], v[110:111], v[174:175]
	v_pk_add_f32 v[108:109], v[108:109], v[172:173]
	global_store_dwordx4 v[116:117], v[108:111], off offset:64


;     __device__ __forceinline__ void operator()(const f32x4 (&acc)[2][2][4][2], const Unit& u, int wr, int wc, int fr, int fq) const {
;     ...
;                         for (int n = 0; n < 2; ++n) { const int c = col0 + bj * HALF + n * 16; const f32x4 b = *(const f32x4*)(rp + c); *(f32x4*)(op + c) = b + acc[ai][bj][m][n]; } } } }
	v_pk_add_f32 v[106:107], v[106:107], v[178:179]
	v_pk_add_f32 v[104:105], v[104:105], v[176:177]
	global_store_dwordx4 v[116:117], v[104:107], off offset:512


;     __device__ __forceinline__ void operator()(const f32x4 (&acc)[2][2][4][2], const Unit& u, int wr, int wc, int fr, int fq) const {
;     ...
;             for (int m = 0; m < 4; ++m) { const int r = row0 + ai * HALF + m * 16;
;                 if (r < lrows) {
;                     const float* rp = (r < nmeta) ? res_meta + (size_t)r * ldc : res_body + (size_t)(r - nmeta) * ldc;
;                     float* op = (r < nmeta) ? out_meta : out_body;
;                     if (op) { op += (r < nmeta) ? (size_t)r * ldc : (size_t)(r - nmeta) * ldc;
; #pragma unroll
;                     for (int bj = 0; bj < 2; ++bj)
; #pragma unroll
;                         for (int n = 0; n < 2; ++n) { const int c = col0 + bj * HALF + n * 16; const f32x4 b = *(const f32x4*)(rp + c); *(f32x4*)(op + c) = b + acc[ai][bj][m][n]; } } } }
	v_pk_add_f32 v[102:103], v[102:103], v[188:189]
	v_pk_add_f32 v[100:101], v[100:101], v[186:187]
	global_store_dwordx4 v[116:117], v[100:103], off offset:576
.LBB0_905:
	s_or_b64 exec, exec, s[0:1]
	s_nop 0
	v_or_b32_e32 v102, 32, v146
	v_cmp_gt_i32_e32 vcc, s2, v102
	s_and_saveexec_b64 s[0:1], vcc
	s_cbranch_execz .LBB0_908
	v_readlane_b32 s24, v254, 11
	v_readlane_b32 s27, v254, 14
	v_readlane_b32 s26, v254, 13
	v_mov_b32_e32 v101, s50
	v_mov_b32_e32 v100, s27
	v_cmp_gt_i32_e32 vcc, 0, v146
	v_mov_b32_e32 v103, s51
	v_readlane_b32 s25, v254, 12
	v_cndmask_b32_e32 v101, v100, v101, vcc
	v_mov_b32_e32 v100, s26
	v_cndmask_b32_e32 v100, v100, v103, vcc
	v_cmp_ne_u64_e64 s[38:39], 0, v[100:101]
	s_and_b64 exec, exec, s[38:39]
	s_cbranch_execz .LBB0_908
	v_readlane_b32 s6, v255, 5
	v_readlane_b32 s7, v255, 6
	v_cndmask_b32_e32 v106, v118, v102, vcc
	v_ashrrev_i32_e32 v139, 31, v138
	v_mov_b32_e32 v103, s7
	v_readlane_b32 s7, v255, 3
	v_lshlrev_b64 v[108:109], 2, v[138:139]
	s_nop 0
	v_mov_b32_e32 v104, s7
	v_cndmask_b32_e32 v105, v103, v104, vcc
	v_mov_b32_e32 v103, s6
	v_readlane_b32 s6, v255, 4
	s_nop 1
	v_mov_b32_e32 v104, s6
	v_cndmask_b32_e32 v104, v103, v104, vcc
	v_ashrrev_i32_e32 v103, 31, v102
	v_cndmask_b32_e32 v107, 0, v103, vcc
	v_lshlrev_b64 v[106:107], 13, v[106:107]
	v_lshl_add_u64 v[104:105], v[104:105], 0, v[106:107]
	v_lshl_add_u64 v[110:111], v[104:105], 0, v[108:109]
	v_lshl_add_u64 v[100:101], v[100:101], 0, v[106:107]
	global_load_dwordx4 v[104:107], v[110:111], off
	global_load_dwordx4 v[172:175], v[110:111], off offset:64
	global_load_dwordx4 v[176:179], v[110:111], off offset:512
	global_load_dwordx4 v[186:189], v[110:111], off offset:576
	v_lshl_add_u64 v[100:101], v[100:101], 0, v[108:109]
	s_waitcnt vmcnt(0)
	v_pk_add_f32 v[94:95], v[94:95], v[106:107]
	v_pk_add_f32 v[92:93], v[92:93], v[104:105]
	global_store_dwordx4 v[100:101], v[92:95], off


;     __device__ __forceinline__ void operator()(const f32x4 (&acc)[2][2][4][2], const Unit& u, int wr, int wc, int fr, int fq) const {
;     ...
;                         for (int n = 0; n < 2; ++n) { const int c = col0 + bj * HALF + n * 16; const f32x4 b = *(const f32x4*)(rp + c); *(f32x4*)(op + c) = b + acc[ai][bj][m][n]; } } } }
	v_pk_add_f32 v[90:91], v[90:91], v[174:175]
	v_pk_add_f32 v[88:89], v[88:89], v[172:173]
	global_store_dwordx4 v[100:101], v[88:91], off offset:64


;     __device__ __forceinline__ void operator()(const f32x4 (&acc)[2][2][4][2], const Unit& u, int wr, int wc, int fr, int fq) const {
;     ...
;                         for (int n = 0; n < 2; ++n) { const int c = col0 + bj * HALF + n * 16; const f32x4 b = *(const f32x4*)(rp + c); *(f32x4*)(op + c) = b + acc[ai][bj][m][n]; } } } }
	v_pk_add_f32 v[86:87], v[86:87], v[178:179]
	v_pk_add_f32 v[84:85], v[84:85], v[176:177]
	global_store_dwordx4 v[100:101], v[84:87], off offset:512


;     __device__ __forceinline__ void operator()(const f32x4 (&acc)[2][2][4][2], const Unit& u, int wr, int wc, int fr, int fq) const {
;     ...
;             for (int m = 0; m < 4; ++m) { const int r = row0 + ai * HALF + m * 16;
;                 if (r < lrows) {
;                     const float* rp = (r < nmeta) ? res_meta + (size_t)r * ldc : res_body + (size_t)(r - nmeta) * ldc;
;                     float* op = (r < nmeta) ? out_meta : out_body;
;                     if (op) { op += (r < nmeta) ? (size_t)r * ldc : (size_t)(r - nmeta) * ldc;
; #pragma unroll
;                     for (int bj = 0; bj < 2; ++bj)
; #pragma unroll
;                         for (int n = 0; n < 2; ++n) { const int c = col0 + bj * HALF + n * 16; const f32x4 b = *(const f32x4*)(rp + c); *(f32x4*)(op + c) = b + acc[ai][bj][m][n]; } } } }
	v_pk_add_f32 v[82:83], v[82:83], v[188:189]
	v_pk_add_f32 v[80:81], v[80:81], v[186:187]
	global_store_dwordx4 v[100:101], v[80:83], off offset:576
.LBB0_908:
	s_or_b64 exec, exec, s[0:1]
	s_nop 0
	v_or_b32_e32 v82, 48, v146
	v_cmp_gt_i32_e32 vcc, s2, v82
	s_and_saveexec_b64 s[0:1], vcc
	s_cbranch_execz .LBB0_911
	v_readlane_b32 s24, v254, 11
	v_readlane_b32 s27, v254, 14
	v_readlane_b32 s26, v254, 13
	v_mov_b32_e32 v81, s50
	v_mov_b32_e32 v80, s27
	v_cmp_gt_i32_e32 vcc, 0, v146
	v_mov_b32_e32 v83, s51
	v_readlane_b32 s25, v254, 12
	v_cndmask_b32_e32 v81, v80, v81, vcc
	v_mov_b32_e32 v80, s26
	v_cndmask_b32_e32 v80, v80, v83, vcc
	v_cmp_ne_u64_e64 s[38:39], 0, v[80:81]
	s_and_b64 exec, exec, s[38:39]
	s_cbranch_execz .LBB0_911
	v_readlane_b32 s6, v255, 5
	v_readlane_b32 s7, v255, 6
	v_readlane_b32 s2, v255, 3
	v_ashrrev_i32_e32 v139, 31, v138
	v_mov_b32_e32 v83, s7
	v_mov_b32_e32 v84, s2
	v_readlane_b32 s2, v255, 4
	v_cndmask_b32_e32 v85, v83, v84, vcc
	v_mov_b32_e32 v83, s6
	v_mov_b32_e32 v84, s2
	v_cndmask_b32_e32 v84, v83, v84, vcc
	v_ashrrev_i32_e32 v83, 31, v82
	v_cndmask_b32_e32 v83, 0, v83, vcc
	v_cndmask_b32_e32 v82, v102, v82, vcc
	v_lshlrev_b64 v[82:83], 13, v[82:83]
	v_lshl_add_u64 v[84:85], v[84:85], 0, v[82:83]
	v_lshlrev_b64 v[88:89], 2, v[138:139]
	v_lshl_add_u64 v[84:85], v[84:85], 0, v[88:89]
	v_lshl_add_u64 v[86:87], v[80:81], 0, v[82:83]
	global_load_dwordx4 v[80:83], v[84:85], off
	global_load_dwordx4 v[172:175], v[84:85], off offset:64
	global_load_dwordx4 v[176:179], v[84:85], off offset:512
	global_load_dwordx4 v[186:189], v[84:85], off offset:576
	s_waitcnt vmcnt(0)
	v_pk_add_f32 v[78:79], v[78:79], v[82:83]
	v_pk_add_f32 v[76:77], v[76:77], v[80:81]
	v_lshl_add_u64 v[80:81], v[86:87], 0, v[88:89]
	global_store_dwordx4 v[80:81], v[76:79], off


;     __device__ __forceinline__ void operator()(const f32x4 (&acc)[2][2][4][2], const Unit& u, int wr, int wc, int fr, int fq) const {
;     ...
;                         for (int n = 0; n < 2; ++n) { const int c = col0 + bj * HALF + n * 16; const f32x4 b = *(const f32x4*)(rp + c); *(f32x4*)(op + c) = b + acc[ai][bj][m][n]; } } } }
	v_pk_add_f32 v[74:75], v[74:75], v[174:175]
	v_pk_add_f32 v[72:73], v[72:73], v[172:173]
	global_store_dwordx4 v[80:81], v[72:75], off offset:64


;     __device__ __forceinline__ void operator()(const f32x4 (&acc)[2][2][4][2], const Unit& u, int wr, int wc, int fr, int fq) const {
;     ...
;                         for (int n = 0; n < 2; ++n) { const int c = col0 + bj * HALF + n * 16; const f32x4 b = *(const f32x4*)(rp + c); *(f32x4*)(op + c) = b + acc[ai][bj][m][n]; } } } }
	v_pk_add_f32 v[70:71], v[70:71], v[178:179]
	v_pk_add_f32 v[68:69], v[68:69], v[176:177]
	global_store_dwordx4 v[80:81], v[68:71], off offset:512


;     __device__ __forceinline__ void operator()(const f32x4 (&acc)[2][2][4][2], const Unit& u, int wr, int wc, int fr, int fq) const {
;     ...
;             for (int m = 0; m < 4; ++m) { const int r = row0 + ai * HALF + m * 16;
;                 if (r < lrows) {
;                     const float* rp = (r < nmeta) ? res_meta + (size_t)r * ldc : res_body + (size_t)(r - nmeta) * ldc;
;                     float* op = (r < nmeta) ? out_meta : out_body;
;                     if (op) { op += (r < nmeta) ? (size_t)r * ldc : (size_t)(r - nmeta) * ldc;
; #pragma unroll
;                     for (int bj = 0; bj < 2; ++bj)
; #pragma unroll
;                         for (int n = 0; n < 2; ++n) { const int c = col0 + bj * HALF + n * 16; const f32x4 b = *(const f32x4*)(rp + c); *(f32x4*)(op + c) = b + acc[ai][bj][m][n]; } } } }
	v_pk_add_f32 v[66:67], v[66:67], v[188:189]
	v_pk_add_f32 v[64:65], v[64:65], v[186:187]
	global_store_dwordx4 v[80:81], v[64:67], off offset:576
.LBB0_911:
	s_or_b64 exec, exec, s[0:1]
	s_movk_i32 s0, 0x3f90
	v_add_u32_e32 v66, 0x80, v146
	v_cmp_gt_i32_e32 vcc, s0, v146
	s_and_saveexec_b64 s[0:1], vcc
	s_cbranch_execz .LBB0_914
	v_readlane_b32 s24, v254, 11
	v_readlane_b32 s27, v254, 14
	s_movk_i32 s2, 0xff90
	v_readlane_b32 s26, v254, 13
	v_mov_b32_e32 v64, s27
	v_mov_b32_e32 v65, s50
	v_cmp_gt_i32_e32 vcc, s2, v146
	v_mov_b32_e32 v67, s51
	v_readlane_b32 s25, v254, 12
	v_cndmask_b32_e32 v65, v64, v65, vcc
	v_mov_b32_e32 v64, s26
	v_cndmask_b32_e32 v64, v64, v67, vcc
	v_cmp_ne_u64_e64 s[38:39], 0, v[64:65]
	s_and_b64 exec, exec, s[38:39]
	s_cbranch_execz .LBB0_914
	v_readlane_b32 s6, v255, 5
	v_readlane_b32 s7, v255, 6
	v_readlane_b32 s2, v255, 3
	v_add_u32_e32 v70, 0x70, v146
	v_mov_b32_e32 v67, s7
	v_mov_b32_e32 v68, s2
	v_readlane_b32 s2, v255, 4
	v_cndmask_b32_e32 v69, v67, v68, vcc
	v_mov_b32_e32 v67, s6
	v_mov_b32_e32 v68, s2
	v_cndmask_b32_e32 v68, v67, v68, vcc
	v_ashrrev_i32_e32 v67, 31, v66
	v_cndmask_b32_e32 v71, 0, v67, vcc
	v_cndmask_b32_e32 v70, v70, v66, vcc
	v_lshlrev_b64 v[70:71], 13, v[70:71]
	v_ashrrev_i32_e32 v139, 31, v138
	v_lshl_add_u64 v[68:69], v[68:69], 0, v[70:71]
	v_lshlrev_b64 v[72:73], 2, v[138:139]
	v_lshl_add_u64 v[74:75], v[68:69], 0, v[72:73]
	v_lshl_add_u64 v[64:65], v[64:65], 0, v[70:71]
	global_load_dwordx4 v[68:71], v[74:75], off
	global_load_dwordx4 v[172:175], v[74:75], off offset:64
	global_load_dwordx4 v[176:179], v[74:75], off offset:512
	global_load_dwordx4 v[186:189], v[74:75], off offset:576
	v_lshl_add_u64 v[64:65], v[64:65], 0, v[72:73]
	s_waitcnt vmcnt(0)
	v_pk_add_f32 v[62:63], v[62:63], v[70:71]
	v_pk_add_f32 v[60:61], v[60:61], v[68:69]
	global_store_dwordx4 v[64:65], v[60:63], off


;     __device__ __forceinline__ void operator()(const f32x4 (&acc)[2][2][4][2], const Unit& u, int wr, int wc, int fr, int fq) const {
;     ...
;                         for (int n = 0; n < 2; ++n) { const int c = col0 + bj * HALF + n * 16; const f32x4 b = *(const f32x4*)(rp + c); *(f32x4*)(op + c) = b + acc[ai][bj][m][n]; } } } }
	v_pk_add_f32 v[58:59], v[58:59], v[174:175]
	v_pk_add_f32 v[56:57], v[56:57], v[172:173]
	global_store_dwordx4 v[64:65], v[56:59], off offset:64


;     __device__ __forceinline__ void operator()(const f32x4 (&acc)[2][2][4][2], const Unit& u, int wr, int wc, int fr, int fq) const {
;     ...
;                         for (int n = 0; n < 2; ++n) { const int c = col0 + bj * HALF + n * 16; const f32x4 b = *(const f32x4*)(rp + c); *(f32x4*)(op + c) = b + acc[ai][bj][m][n]; } } } }
	v_pk_add_f32 v[54:55], v[54:55], v[178:179]
	v_pk_add_f32 v[52:53], v[52:53], v[176:177]
	global_store_dwordx4 v[64:65], v[52:55], off offset:512


;     __device__ __forceinline__ void operator()(const f32x4 (&acc)[2][2][4][2], const Unit& u, int wr, int wc, int fr, int fq) const {
;     ...
;             for (int m = 0; m < 4; ++m) { const int r = row0 + ai * HALF + m * 16;
;                 if (r < lrows) {
;                     const float* rp = (r < nmeta) ? res_meta + (size_t)r * ldc : res_body + (size_t)(r - nmeta) * ldc;
;                     float* op = (r < nmeta) ? out_meta : out_body;
;                     if (op) { op += (r < nmeta) ? (size_t)r * ldc : (size_t)(r - nmeta) * ldc;
; #pragma unroll
;                     for (int bj = 0; bj < 2; ++bj)
; #pragma unroll
;                         for (int n = 0; n < 2; ++n) { const int c = col0 + bj * HALF + n * 16; const f32x4 b = *(const f32x4*)(rp + c); *(f32x4*)(op + c) = b + acc[ai][bj][m][n]; } } } }
	v_pk_add_f32 v[50:51], v[50:51], v[188:189]
	v_pk_add_f32 v[48:49], v[48:49], v[186:187]
	global_store_dwordx4 v[64:65], v[48:51], off offset:576
.LBB0_914:
	s_or_b64 exec, exec, s[0:1]
	s_movk_i32 s0, 0x3f80
	v_add_u32_e32 v50, 0x90, v146
	v_cmp_gt_i32_e32 vcc, s0, v146
	s_and_saveexec_b64 s[0:1], vcc
	s_cbranch_execz .LBB0_917
	v_readlane_b32 s24, v254, 11
	v_readlane_b32 s27, v254, 14
	s_movk_i32 s2, 0xff80
	v_readlane_b32 s26, v254, 13
	v_mov_b32_e32 v48, s27
	v_mov_b32_e32 v49, s50
	v_cmp_gt_i32_e32 vcc, s2, v146
	v_mov_b32_e32 v51, s51
	v_readlane_b32 s25, v254, 12
	v_cndmask_b32_e32 v49, v48, v49, vcc
	v_mov_b32_e32 v48, s26
	v_cndmask_b32_e32 v48, v48, v51, vcc
	v_cmp_ne_u64_e64 s[38:39], 0, v[48:49]
	s_and_b64 exec, exec, s[38:39]
	s_cbranch_execz .LBB0_917
	v_readlane_b32 s6, v255, 5
	v_readlane_b32 s7, v255, 6
	v_readlane_b32 s2, v255, 3
	v_cndmask_b32_e32 v54, v66, v50, vcc
	v_mov_b32_e32 v51, s7
	v_mov_b32_e32 v52, s2
	v_readlane_b32 s2, v255, 4
	v_cndmask_b32_e32 v53, v51, v52, vcc
	v_mov_b32_e32 v51, s6
	v_mov_b32_e32 v52, s2
	v_cndmask_b32_e32 v52, v51, v52, vcc
	v_ashrrev_i32_e32 v51, 31, v50
	v_cndmask_b32_e32 v55, 0, v51, vcc
	v_lshlrev_b64 v[54:55], 13, v[54:55]
	v_ashrrev_i32_e32 v139, 31, v138
	v_lshl_add_u64 v[52:53], v[52:53], 0, v[54:55]
	v_lshlrev_b64 v[56:57], 2, v[138:139]
	v_lshl_add_u64 v[58:59], v[52:53], 0, v[56:57]
	v_lshl_add_u64 v[48:49], v[48:49], 0, v[54:55]
	global_load_dwordx4 v[52:55], v[58:59], off
	global_load_dwordx4 v[172:175], v[58:59], off offset:64
	global_load_dwordx4 v[176:179], v[58:59], off offset:512
	global_load_dwordx4 v[186:189], v[58:59], off offset:576
	v_lshl_add_u64 v[48:49], v[48:49], 0, v[56:57]
	s_waitcnt vmcnt(0)
	v_pk_add_f32 v[46:47], v[46:47], v[54:55]
	v_pk_add_f32 v[44:45], v[44:45], v[52:53]
	global_store_dwordx4 v[48:49], v[44:47], off


;     __device__ __forceinline__ void operator()(const f32x4 (&acc)[2][2][4][2], const Unit& u, int wr, int wc, int fr, int fq) const {
;     ...
;                         for (int n = 0; n < 2; ++n) { const int c = col0 + bj * HALF + n * 16; const f32x4 b = *(const f32x4*)(rp + c); *(f32x4*)(op + c) = b + acc[ai][bj][m][n]; } } } }
	v_pk_add_f32 v[42:43], v[42:43], v[174:175]
	v_pk_add_f32 v[40:41], v[40:41], v[172:173]
	global_store_dwordx4 v[48:49], v[40:43], off offset:64


;     __device__ __forceinline__ void operator()(const f32x4 (&acc)[2][2][4][2], const Unit& u, int wr, int wc, int fr, int fq) const {
;     ...
;                         for (int n = 0; n < 2; ++n) { const int c = col0 + bj * HALF + n * 16; const f32x4 b = *(const f32x4*)(rp + c); *(f32x4*)(op + c) = b + acc[ai][bj][m][n]; } } } }
	v_pk_add_f32 v[38:39], v[38:39], v[178:179]
	v_pk_add_f32 v[36:37], v[36:37], v[176:177]
	global_store_dwordx4 v[48:49], v[36:39], off offset:512


;     __device__ __forceinline__ void operator()(const f32x4 (&acc)[2][2][4][2], const Unit& u, int wr, int wc, int fr, int fq) const {
;     ...
;             for (int m = 0; m < 4; ++m) { const int r = row0 + ai * HALF + m * 16;
;                 if (r < lrows) {
;                     const float* rp = (r < nmeta) ? res_meta + (size_t)r * ldc : res_body + (size_t)(r - nmeta) * ldc;
;                     float* op = (r < nmeta) ? out_meta : out_body;
;                     if (op) { op += (r < nmeta) ? (size_t)r * ldc : (size_t)(r - nmeta) * ldc;
; #pragma unroll
;                     for (int bj = 0; bj < 2; ++bj)
; #pragma unroll
;                         for (int n = 0; n < 2; ++n) { const int c = col0 + bj * HALF + n * 16; const f32x4 b = *(const f32x4*)(rp + c); *(f32x4*)(op + c) = b + acc[ai][bj][m][n]; } } } }
	v_pk_add_f32 v[34:35], v[34:35], v[188:189]
	v_pk_add_f32 v[32:33], v[32:33], v[186:187]
	global_store_dwordx4 v[48:49], v[32:35], off offset:576
.LBB0_917:
	s_or_b64 exec, exec, s[0:1]
	s_movk_i32 s0, 0x3f70
	v_add_u32_e32 v34, 0xa0, v146
	v_cmp_gt_i32_e32 vcc, s0, v146
	s_and_saveexec_b64 s[0:1], vcc
	s_cbranch_execz .LBB0_920
	v_readlane_b32 s24, v254, 11
	v_readlane_b32 s27, v254, 14
	s_movk_i32 s2, 0xff70
	v_readlane_b32 s26, v254, 13
	v_mov_b32_e32 v32, s27
	v_mov_b32_e32 v33, s50
	v_cmp_gt_i32_e32 vcc, s2, v146
	v_mov_b32_e32 v35, s51
	v_readlane_b32 s25, v254, 12
	v_cndmask_b32_e32 v33, v32, v33, vcc
	v_mov_b32_e32 v32, s26
	v_cndmask_b32_e32 v32, v32, v35, vcc
	v_cmp_ne_u64_e64 s[38:39], 0, v[32:33]
	s_and_b64 exec, exec, s[38:39]
	s_cbranch_execz .LBB0_920
	v_readlane_b32 s6, v255, 5
	v_readlane_b32 s7, v255, 6
	v_readlane_b32 s2, v255, 3
	v_cndmask_b32_e32 v38, v50, v34, vcc
	v_mov_b32_e32 v35, s7
	v_mov_b32_e32 v36, s2
	v_readlane_b32 s2, v255, 4
	v_cndmask_b32_e32 v37, v35, v36, vcc
	v_mov_b32_e32 v35, s6
	v_mov_b32_e32 v36, s2
	v_cndmask_b32_e32 v36, v35, v36, vcc
	v_ashrrev_i32_e32 v35, 31, v34
	v_cndmask_b32_e32 v39, 0, v35, vcc
	v_lshlrev_b64 v[38:39], 13, v[38:39]
	v_ashrrev_i32_e32 v139, 31, v138
	v_lshl_add_u64 v[36:37], v[36:37], 0, v[38:39]
	v_lshlrev_b64 v[40:41], 2, v[138:139]
	v_lshl_add_u64 v[42:43], v[36:37], 0, v[40:41]
	v_lshl_add_u64 v[32:33], v[32:33], 0, v[38:39]
	global_load_dwordx4 v[36:39], v[42:43], off
	global_load_dwordx4 v[172:175], v[42:43], off offset:64
	global_load_dwordx4 v[176:179], v[42:43], off offset:512
	global_load_dwordx4 v[186:189], v[42:43], off offset:576
	v_lshl_add_u64 v[32:33], v[32:33], 0, v[40:41]
	s_waitcnt vmcnt(0)
	v_pk_add_f32 v[30:31], v[30:31], v[38:39]
	v_pk_add_f32 v[28:29], v[28:29], v[36:37]
	global_store_dwordx4 v[32:33], v[28:31], off


;     __device__ __forceinline__ void operator()(const f32x4 (&acc)[2][2][4][2], const Unit& u, int wr, int wc, int fr, int fq) const {
;     ...
;                         for (int n = 0; n < 2; ++n) { const int c = col0 + bj * HALF + n * 16; const f32x4 b = *(const f32x4*)(rp + c); *(f32x4*)(op + c) = b + acc[ai][bj][m][n]; } } } }
	v_pk_add_f32 v[26:27], v[26:27], v[174:175]
	v_pk_add_f32 v[24:25], v[24:25], v[172:173]
	global_store_dwordx4 v[32:33], v[24:27], off offset:64


;     __device__ __forceinline__ void operator()(const f32x4 (&acc)[2][2][4][2], const Unit& u, int wr, int wc, int fr, int fq) const {
;     ...
;                         for (int n = 0; n < 2; ++n) { const int c = col0 + bj * HALF + n * 16; const f32x4 b = *(const f32x4*)(rp + c); *(f32x4*)(op + c) = b + acc[ai][bj][m][n]; } } } }
	v_pk_add_f32 v[22:23], v[22:23], v[178:179]
	v_pk_add_f32 v[20:21], v[20:21], v[176:177]
	global_store_dwordx4 v[32:33], v[20:23], off offset:512


;     __device__ __forceinline__ void operator()(const f32x4 (&acc)[2][2][4][2], const Unit& u, int wr, int wc, int fr, int fq) const {
;     ...
;             for (int m = 0; m < 4; ++m) { const int r = row0 + ai * HALF + m * 16;
;                 if (r < lrows) {
;                     const float* rp = (r < nmeta) ? res_meta + (size_t)r * ldc : res_body + (size_t)(r - nmeta) * ldc;
;                     float* op = (r < nmeta) ? out_meta : out_body;
;                     if (op) { op += (r < nmeta) ? (size_t)r * ldc : (size_t)(r - nmeta) * ldc;
; #pragma unroll
;                     for (int bj = 0; bj < 2; ++bj)
; #pragma unroll
;                         for (int n = 0; n < 2; ++n) { const int c = col0 + bj * HALF + n * 16; const f32x4 b = *(const f32x4*)(rp + c); *(f32x4*)(op + c) = b + acc[ai][bj][m][n]; } } } }
	v_pk_add_f32 v[18:19], v[18:19], v[188:189]
	v_pk_add_f32 v[16:17], v[16:17], v[186:187]
	global_store_dwordx4 v[32:33], v[16:19], off offset:576
.LBB0_920:
	s_or_b64 exec, exec, s[0:1]
	s_movk_i32 s0, 0x3f60
	v_cmp_gt_i32_e32 vcc, s0, v146
	s_and_saveexec_b64 s[0:1], vcc
	s_cbranch_execz .LBB0_923
	v_readlane_b32 s24, v254, 11
	v_readlane_b32 s27, v254, 14
	s_movk_i32 s2, 0xff60
	v_readlane_b32 s26, v254, 13
	v_mov_b32_e32 v16, s27
	v_mov_b32_e32 v17, s50
	v_cmp_gt_i32_e32 vcc, s2, v146
	v_mov_b32_e32 v18, s51
	v_readlane_b32 s25, v254, 12
	v_cndmask_b32_e32 v17, v16, v17, vcc
	v_mov_b32_e32 v16, s26
	v_cndmask_b32_e32 v16, v16, v18, vcc
	v_cmp_ne_u64_e64 s[38:39], 0, v[16:17]
	s_and_b64 exec, exec, s[38:39]
	s_cbranch_execz .LBB0_923
	v_readlane_b32 s6, v255, 5
	v_readlane_b32 s7, v255, 6
	v_readlane_b32 s2, v255, 3
	v_add_u32_e32 v20, 0xb0, v146
	v_mov_b32_e32 v18, s7
	v_mov_b32_e32 v19, s2
	v_readlane_b32 s2, v255, 4
	v_cndmask_b32_e32 v19, v18, v19, vcc
	v_mov_b32_e32 v18, s6
	v_mov_b32_e32 v21, s2
	v_cndmask_b32_e32 v18, v18, v21, vcc
	v_ashrrev_i32_e32 v21, 31, v20
	v_cndmask_b32_e32 v21, 0, v21, vcc
	v_cndmask_b32_e32 v20, v34, v20, vcc
	v_lshlrev_b64 v[20:21], 13, v[20:21]
	v_ashrrev_i32_e32 v139, 31, v138
	v_lshl_add_u64 v[18:19], v[18:19], 0, v[20:21]
	v_lshlrev_b64 v[22:23], 2, v[138:139]
	v_lshl_add_u64 v[24:25], v[18:19], 0, v[22:23]
	v_lshl_add_u64 v[20:21], v[16:17], 0, v[20:21]
	global_load_dwordx4 v[16:19], v[24:25], off
	global_load_dwordx4 v[172:175], v[24:25], off offset:64
	global_load_dwordx4 v[176:179], v[24:25], off offset:512
	global_load_dwordx4 v[186:189], v[24:25], off offset:576
	s_waitcnt vmcnt(0)
	v_pk_add_f32 v[14:15], v[14:15], v[18:19]
	v_pk_add_f32 v[12:13], v[12:13], v[16:17]
	v_lshl_add_u64 v[16:17], v[20:21], 0, v[22:23]
	global_store_dwordx4 v[16:17], v[12:15], off


;     __device__ __forceinline__ void operator()(const f32x4 (&acc)[2][2][4][2], const Unit& u, int wr, int wc, int fr, int fq) const {
;     ...
;                         for (int n = 0; n < 2; ++n) { const int c = col0 + bj * HALF + n * 16; const f32x4 b = *(const f32x4*)(rp + c); *(f32x4*)(op + c) = b + acc[ai][bj][m][n]; } } } }
	v_pk_add_f32 v[10:11], v[10:11], v[174:175]
	v_pk_add_f32 v[8:9], v[8:9], v[172:173]
	global_store_dwordx4 v[16:17], v[8:11], off offset:64


;     __device__ __forceinline__ void operator()(const f32x4 (&acc)[2][2][4][2], const Unit& u, int wr, int wc, int fr, int fq) const {
;     ...
;                         for (int n = 0; n < 2; ++n) { const int c = col0 + bj * HALF + n * 16; const f32x4 b = *(const f32x4*)(rp + c); *(f32x4*)(op + c) = b + acc[ai][bj][m][n]; } } } }
	v_pk_add_f32 v[6:7], v[6:7], v[178:179]
	v_pk_add_f32 v[4:5], v[4:5], v[176:177]
	global_store_dwordx4 v[16:17], v[4:7], off offset:512


;     __device__ __forceinline__ void operator()(const f32x4 (&acc)[2][2][4][2], const Unit& u, int wr, int wc, int fr, int fq) const {
;     ...
;                         for (int n = 0; n < 2; ++n) { const int c = col0 + bj * HALF + n * 16; const f32x4 b = *(const f32x4*)(rp + c); *(f32x4*)(op + c) = b + acc[ai][bj][m][n]; } } } }
	v_pk_add_f32 v[2:3], v[2:3], v[188:189]
	v_pk_add_f32 v[0:1], v[0:1], v[186:187]
	global_store_dwordx4 v[16:17], v[0:3], off offset:576
